# FFN-up fast epilogue: halo rows published and fetched with two dwordx4 instead of four dwordx2
# speedup vs baseline: 1.0096x; 1.0096x over previous
;     __device__ __forceinline__ void operator()(f32x4 (&acc)[2][2][4][2], const pg8::Unit& u, int wr, int wc, int fr, int fq) const {
;     ...
;                 if (wr == 1 && (u.pm & 7) != 7) { unsigned long long* hp = HALO + ((size_t)(u.pm * 96 + u.pn) * 2 + (fr - 14)) * 64 + (cl0 >> 1);
; #pragma unroll
;                     for (int n = 0; n < 2; ++n) { const f32x4 g = acc[1][0][3][n];
;                         __hip_atomic_store(hp + 2 * n, ((unsigned long long)__float_as_uint(g[1]) << 32) | __float_as_uint(g[0]), __ATOMIC_RELAXED, __HIP_MEMORY_SCOPE_AGENT);
;                         __hip_atomic_store(hp + 2 * n + 1, ((unsigned long long)__float_as_uint(g[3]) << 32) | __float_as_uint(g[2]), __ATOMIC_RELAXED, __HIP_MEMORY_SCOPE_AGENT); } }
.Lf8_pubhalo:
	v_lshl_add_u64 v[166:167], v[180:181], 0, s[48:49]
	global_store_dwordx4 v[166:167], v[26:29], off sc1
	global_store_dwordx4 v[166:167], v[18:21], off offset:16 sc1

;     __device__ __forceinline__ void operator()(f32x4 (&acc)[2][2][4][2], const pg8::Unit& u, int wr, int wc, int fr, int fq) const {
;     ...
;                 else if ((u.pm & 7) != 0) { unsigned* fl = HFLAG + (u.pm - 1) * 96 + u.pn; unsigned sp = 0;
;                     while ((unsigned)__builtin_amdgcn_readfirstlane(__hip_atomic_load(fl, __ATOMIC_RELAXED, __HIP_MEMORY_SCOPE_AGENT)) < 4u) { __builtin_amdgcn_s_sleep(2);
;                         if ((++sp & 1023u) == 0u) { if (__hip_atomic_load(tmo, __ATOMIC_RELAXED, __HIP_MEMORY_SCOPE_AGENT) != 0u) break; if (sp > (1u << 22)) { __hip_atomic_store(tmo, 1u, __ATOMIC_RELAXED, __HIP_MEMORY_SCOPE_AGENT); break; } } }
;                     if (fr >= 14) { const unsigned long long* hp = HALO + ((size_t)((u.pm - 1) * 96 + u.pn) * 2 + (fr - 14)) * 64 + (cl0 >> 1);
; #pragma unroll
;                         for (int n = 0; n < 2; ++n) { const unsigned long long a = __hip_atomic_load(hp + 2 * n, __ATOMIC_RELAXED, __HIP_MEMORY_SCOPE_AGENT), b2 = __hip_atomic_load(hp + 2 * n + 1, __ATOMIC_RELAXED, __HIP_MEMORY_SCOPE_AGENT);
;                             hal[n] = (f32x4){__uint_as_float((unsigned)a), __uint_as_float((unsigned)(a >> 32)), __uint_as_float((unsigned)b2), __uint_as_float((unsigned)(b2 >> 32))}; } } } }
.Lf8_polled:
	s_and_saveexec_b64 s[44:45], s[46:47]
	v_lshl_add_u64 v[224:225], v[180:181], 0, s[72:73]
	global_load_dwordx4 v[146:149], v[224:225], off sc1
	global_load_dwordx4 v[150:153], v[224:225], off offset:16 sc1
	s_mov_b64 exec, s[44:45]
	s_mov_b32 s85, 1
